# levers 1/8: stick-breaking tile block keeps the 8 K-fragment LDS reads of its first QK section in flight with counted waits (was read pair / wait / MFMA pair)
# speedup vs baseline: 1.0010x; 1.0010x over previous
.LBB0_465:
	s_cmp_ge_i32 s23, s4
	s_cselect_b64 s[16:17], -1, 0
	s_or_b64 s[16:17], s[16:17], s[14:15]
	s_and_b64 vcc, exec, s[16:17]
	s_cbranch_vccnz .LBB0_467
	s_add_i32 s98, s23, 94
	s_cmp_lt_i32 s98, s4
	s_cbranch_scc0 .Lsb_near
	v_add3_u32 v130, s18, v192, v205
	ds_read_b128 v[132:135], v130 offset:8704
	ds_read_b128 v[136:139], v130 offset:8736
	ds_read_b128 v[140:143], v130 offset:8768
	ds_read_b128 v[144:147], v130 offset:8800
	ds_read_b128 v[164:167], v130 offset:8832
	ds_read_b128 v[168:171], v130 offset:8864
	ds_read_b128 v[172:175], v130 offset:8896
	ds_read_b128 v[176:179], v130 offset:8928
	ds_read_b128 v[208:211], v130 offset:224
	v_add3_u32 v207, s22, v204, v206
	s_waitcnt lgkmcnt(8)
	v_mfma_f32_32x32x16_bf16 v[66:81], v[132:135], v[82:85], 0
	s_waitcnt lgkmcnt(7)
	v_mfma_f32_32x32x16_bf16 v[66:81], v[136:139], v[86:89], v[66:81]
	s_waitcnt lgkmcnt(6)
	v_mfma_f32_32x32x16_bf16 v[66:81], v[140:143], v[90:93], v[66:81]
	s_waitcnt lgkmcnt(5)
	v_mfma_f32_32x32x16_bf16 v[66:81], v[144:147], v[94:97], v[66:81]
	s_waitcnt lgkmcnt(4)
	v_mfma_f32_32x32x16_bf16 v[66:81], v[164:167], v[98:101], v[66:81]
	s_waitcnt lgkmcnt(3)
	v_mfma_f32_32x32x16_bf16 v[66:81], v[168:171], v[102:105], v[66:81]
	s_waitcnt lgkmcnt(2)
	v_mfma_f32_32x32x16_bf16 v[66:81], v[172:175], v[106:109], v[66:81]
	s_waitcnt lgkmcnt(1)
	v_mfma_f32_32x32x16_bf16 v[66:81], v[176:179], v[110:113], v[66:81]
	s_nop 11
	v_mov_b32_e32 v64, v66
	v_mov_b32_e32 v65, v68
	v_mov_b32_e32 v68, v67
	v_mul_f32_e32 v132, s68, v64
	v_mul_f32_e32 v133, s68, v65
	v_mov_b32_e32 v66, v70
	v_mul_f32_e32 v134, s68, v68
	v_mul_f32_e32 v135, s68, v69
	v_mul_f32_e64 v70, |v132|, s54
	v_mov_b32_e32 v67, v72
	v_mul_f32_e64 v72, |v134|, s54
	v_exp_f32_e32 v70, v70
	v_mul_f32_e64 v131, |v133|, s54
	v_exp_f32_e32 v72, v72
	v_mul_f32_e64 v138, |v135|, s54
	v_exp_f32_e32 v131, v131
	v_mul_f32_e32 v136, s68, v66
	v_mul_f32_e32 v137, s68, v67
	v_exp_f32_e32 v138, v138
	v_mul_f32_e64 v139, |v136|, s54
	v_add_f32_e32 v70, 1.0, v70
	v_exp_f32_e32 v139, v139
	v_add_f32_e32 v72, 1.0, v72
	v_add_f32_e32 v131, 1.0, v131
	v_add_f32_e32 v138, 1.0, v138
	v_log_f32_e32 v70, v70
	v_add_f32_e32 v139, 1.0, v139
	v_log_f32_e32 v72, v72
	v_log_f32_e32 v131, v131
	v_log_f32_e32 v138, v138
	v_mov_b32_e32 v142, v139
	v_mul_f32_e32 v139, 0x3f317217, v70
	v_mul_f32_e32 v140, 0x3f317217, v72
	v_fma_f32 v139, v70, s86, -v139
	v_mul_f32_e32 v141, 0x3f317217, v131
	v_fma_f32 v140, v72, s86, -v140
	v_fmac_f32_e32 v139, 0x3377d1cf, v70
	v_mul_f32_e32 v143, 0x3f317217, v138
	v_fma_f32 v141, v131, s86, -v141
	v_fmac_f32_e32 v140, 0x3377d1cf, v72
	v_fmac_f32_e32 v139, 0x3f317217, v70
	v_fma_f32 v143, v138, s86, -v143
	v_fmac_f32_e32 v141, 0x3377d1cf, v131
	v_fmac_f32_e32 v140, 0x3f317217, v72
	v_fmac_f32_e32 v143, 0x3377d1cf, v138
	v_fmac_f32_e32 v141, 0x3f317217, v131
	v_fmac_f32_e32 v143, 0x3f317217, v138
	v_min_f32_e32 v132, 0, v132
	v_min_f32_e32 v133, 0, v133
	v_sub_f32_e32 v166, v132, v139
	v_sub_f32_e32 v167, v133, v141
	v_fma_f32 v174, -v64, s68, v166
	v_fma_f32 v175, -v65, s68, v167
	v_log_f32_e32 v65, v142
	v_min_f32_e32 v134, 0, v134
	v_min_f32_e32 v135, 0, v135
	v_sub_f32_e32 v164, v134, v140
	v_sub_f32_e32 v165, v135, v143
	v_mov_b32_e32 v72, v71
	v_fma_f32 v172, -v68, s68, v164
	v_fma_f32 v173, -v69, s68, v165
	v_mul_f32_e32 v68, 0x3f317217, v65
	v_fma_f32 v70, v65, s86, -v68
	v_mul_f32_e32 v68, s68, v72
	v_mul_f32_e32 v69, s68, v73
	v_fmac_f32_e32 v70, 0x3377d1cf, v65
	v_mul_f32_e64 v71, |v68|, s54
	v_exp_f32_e32 v71, v71
	v_fmac_f32_e32 v70, 0x3f317217, v65
	v_mul_f32_e64 v131, |v137|, s54
	v_exp_f32_e32 v131, v131
	v_mov_b32_e32 v65, v70
	v_add_f32_e32 v70, 1.0, v71
	v_mul_f32_e64 v133, |v69|, s54
	v_exp_f32_e32 v133, v133
	v_log_f32_e32 v71, v70
	v_mov_b32_e32 v70, v65
	v_min_f32_e32 v64, 0, v136
	v_mul_f32_e32 v65, 0x3f317217, v71
	v_fma_f32 v65, v71, s86, -v65
	v_fmac_f32_e32 v65, 0x3377d1cf, v71
	v_fmac_f32_e32 v65, 0x3f317217, v71
	v_min_f32_e32 v68, 0, v68
	v_min_f32_e32 v69, 0, v69
	v_add_f32_e32 v71, 1.0, v131
	v_mov_b32_e32 v140, v78
	v_mov_b32_e32 v141, v80
	v_log_f32_e32 v71, v71
	v_mov_b32_e32 v132, v65
	v_min_f32_e32 v65, 0, v137
	v_mul_f32_e32 v131, 0x3f317217, v71
	v_fma_f32 v131, v71, s86, -v131
	v_fmac_f32_e32 v131, 0x3377d1cf, v71
	v_fmac_f32_e32 v131, 0x3f317217, v71
	v_mul_f32_e32 v142, s68, v140
	v_mul_f32_e32 v143, s68, v141
	v_mov_b32_e32 v80, v79
	v_mov_b32_e32 v71, v131
	v_add_f32_e32 v131, 1.0, v133
	v_sub_f32_e32 v168, v64, v70
	v_sub_f32_e32 v169, v65, v71
	v_log_f32_e32 v131, v131
	v_fma_f32 v176, -v66, s68, v168
	v_fma_f32 v177, -v67, s68, v169
	v_mul_f32_e32 v144, s68, v80
	v_mul_f32_e32 v145, s68, v81
	v_mul_f32_e32 v64, 0x3f317217, v131
	v_fma_f32 v70, v131, s86, -v64
	v_mov_b32_e32 v64, v74
	v_mul_f32_e32 v66, s68, v64
	v_mul_f32_e32 v67, s68, v76
	v_fmac_f32_e32 v70, 0x3377d1cf, v131
	v_mul_f32_e64 v71, |v66|, s54
	v_exp_f32_e32 v71, v71
	v_fmac_f32_e32 v70, 0x3f317217, v131
	v_min_f32_e32 v66, 0, v66
	v_mov_b32_e32 v133, v70
	v_add_f32_e32 v70, 1.0, v71
	v_sub_f32_e32 v170, v68, v132
	v_sub_f32_e32 v171, v69, v133
	ds_read_b128 v[132:135], v130 offset:32
	v_log_f32_e32 v70, v70
	v_fma_f32 v178, -v72, s68, v170
	v_fma_f32 v179, -v73, s68, v171
	v_mul_f32_e64 v73, |v67|, s54
	v_exp_f32_e32 v73, v73
	v_mul_f32_e32 v68, 0x3f317217, v70
	v_fma_f32 v71, v70, s86, -v68
	v_mul_f32_e32 v68, s68, v75
	v_mul_f32_e32 v69, s68, v77
	v_fmac_f32_e32 v71, 0x3377d1cf, v70
	v_mul_f32_e64 v72, |v68|, s54
	v_exp_f32_e32 v72, v72
	v_fmac_f32_e32 v71, 0x3f317217, v70
	v_mul_f32_e64 v74, |v69|, s54
	v_exp_f32_e32 v74, v74
	v_mov_b32_e32 v70, v71
	v_add_f32_e32 v71, 1.0, v72
	v_min_f32_e32 v67, 0, v67
	v_min_f32_e32 v68, 0, v68
	v_log_f32_e32 v71, v71
	v_mov_b32_e32 v70, v70
	v_min_f32_e32 v69, 0, v69
	v_mul_f32_e32 v72, 0x3f317217, v71
	v_fma_f32 v72, v71, s86, -v72
	v_fmac_f32_e32 v72, 0x3377d1cf, v71
	v_fmac_f32_e32 v72, 0x3f317217, v71
	s_nop 1
	v_mov_b32_e32 v71, v72
	v_add_f32_e32 v72, 1.0, v73
	s_nop 1
	v_log_f32_e32 v73, v72
	v_mov_b32_e32 v72, v71
	v_mul_f32_e32 v71, 0x3f317217, v73
	v_fma_f32 v71, v73, s86, -v71
	v_fmac_f32_e32 v71, 0x3377d1cf, v73
	v_fmac_f32_e32 v71, 0x3f317217, v73
	s_nop 1
	v_add_f32_e32 v73, 1.0, v74
	v_sub_f32_e32 v180, v66, v70
	v_sub_f32_e32 v181, v67, v71
	v_mul_f32_e64 v70, |v143|, s54
	v_log_f32_e32 v73, v73
	v_fma_f32 v184, -v64, s68, v180
	v_fma_f32 v185, -v76, s68, v181
	v_mul_f32_e64 v65, |v142|, s54
	v_exp_f32_e32 v65, v65
	v_mul_f32_e32 v64, 0x3f317217, v73
	v_fma_f32 v64, v73, s86, -v64
	v_fmac_f32_e32 v64, 0x3377d1cf, v73
	v_fmac_f32_e32 v64, 0x3f317217, v73
	v_exp_f32_e32 v131, v70
	v_mov_b32_e32 v73, v64
	v_add_f32_e32 v64, 1.0, v65
	v_mul_f32_e64 v66, |v144|, s54
	v_exp_f32_e32 v66, v66
	v_log_f32_e32 v64, v64
	v_sub_f32_e32 v182, v68, v72
	v_sub_f32_e32 v183, v69, v73
	v_add_f32_e32 v131, 1.0, v131
	v_fma_f32 v186, -v75, s68, v182
	v_fma_f32 v187, -v77, s68, v183
	v_mul_f32_e32 v65, 0x3f317217, v64
	v_fma_f32 v65, v64, s86, -v65
	v_fmac_f32_e32 v65, 0x3377d1cf, v64
	v_fmac_f32_e32 v65, 0x3f317217, v64
	v_min_f32_e32 v142, 0, v142
	v_min_f32_e32 v143, 0, v143
	v_mov_b32_e32 v64, v65
	v_add_f32_e32 v65, 1.0, v66
	v_min_f32_e32 v144, 0, v144
	v_log_f32_e32 v68, v65
	v_mov_b32_e32 v146, v64
	ds_read_b128 v[64:67], v130
	v_mul_f32_e32 v69, 0x3f317217, v68
	v_fma_f32 v69, v68, s86, -v69
	v_fmac_f32_e32 v69, 0x3377d1cf, v68
	v_fmac_f32_e32 v69, 0x3f317217, v68
	s_nop 0
	v_mov_b32_e32 v147, v69
	s_waitcnt lgkmcnt(0)
	v_mfma_f32_32x32x16_bf16 v[64:79], v[64:67], v[82:85], 0
	v_mov_b32_e32 v148, v147
	s_nop 0
	ds_read_b128 v[136:139], v130 offset:64
	v_log_f32_e32 v131, v131
	v_mfma_f32_32x32x16_bf16 v[64:79], v[132:135], v[86:89], v[64:79]
	v_mul_f32_e32 v132, 0x3f317217, v131
	v_fma_f32 v147, v131, s86, -v132
	ds_read_b128 v[132:135], v130 offset:96
	v_fmac_f32_e32 v147, 0x3377d1cf, v131
	v_fmac_f32_e32 v147, 0x3f317217, v131
	s_waitcnt lgkmcnt(1)
	v_mfma_f32_32x32x16_bf16 v[64:79], v[136:139], v[90:93], v[64:79]
	v_mul_f32_e64 v137, |v145|, s54
	v_exp_f32_e32 v149, v137
	ds_read_b128 v[136:139], v130 offset:128
	s_waitcnt lgkmcnt(1)
	v_mfma_f32_32x32x16_bf16 v[64:79], v[132:135], v[94:97], v[64:79]
	v_add_f32_e32 v131, 1.0, v149
	v_add_f32_e64 v188, v142, -v146
	v_add_f32_e64 v189, v143, -v147
	v_min_f32_e32 v145, 0, v145
	ds_read_b128 v[132:135], v130 offset:160
	s_waitcnt lgkmcnt(1)
	v_mfma_f32_32x32x16_bf16 v[64:79], v[136:139], v[98:101], v[64:79]
	v_log_f32_e32 v131, v131
	v_fma_f32 v212, -v140, s68, v188
	v_fma_f32 v213, -v141, s68, v189
	v_mul_f32_e32 v136, 0x3f317217, v131
	v_fma_f32 v140, v131, s86, -v136
	ds_read_b128 v[136:139], v130 offset:192
	s_waitcnt lgkmcnt(1)
	v_mfma_f32_32x32x16_bf16 v[64:79], v[132:135], v[102:105], v[64:79]
	v_fmac_f32_e32 v140, 0x3377d1cf, v131
	v_fmac_f32_e32 v140, 0x3f317217, v131
	s_nop 0
	s_waitcnt lgkmcnt(0)
	v_mfma_f32_32x32x16_bf16 v[64:79], v[136:139], v[106:109], v[64:79]
	v_add_f32_e64 v190, v144, -v148
	v_add_f32_e64 v191, v145, -v140
	ds_read_b64_tr_b16 v[146:147], v207 offset:45056
	ds_read_b64_tr_b16 v[142:143], v207 offset:45120
	ds_read_b64_tr_b16 v[138:139], v207 offset:45184
	ds_read_b64_tr_b16 v[134:135], v207 offset:45248
	ds_read_b64_tr_b16 v[148:149], v207 offset:47616
	ds_read_b64_tr_b16 v[144:145], v207 offset:47680
	ds_read_b64_tr_b16 v[140:141], v207 offset:47744
	ds_read_b64_tr_b16 v[136:137], v207 offset:47808
	ds_read_b64_tr_b16 v[130:131], v207 offset:50176
	ds_read_b64_tr_b16 v[132:133], v207 offset:52736
	v_fma_f32 v216, -v80, s68, v190
	v_fma_f32 v217, -v81, s68, v191
	v_mfma_f32_32x32x16_bf16 v[64:79], v[208:211], v[110:113], v[64:79]
	v_mov_b32_e32 v80, v174
	v_mov_b32_e32 v81, v175
	v_mov_b32_e32 v174, v172
	v_mov_b32_e32 v175, v173
	v_add_f32_e32 v80, v80, v174
	v_add_f32_e32 v81, v81, v175
	v_add_f32_e32 v172, v80, v81
	v_add_f32_e32 v173, v81, v80
	v_mov_b32_e32 v210, v216
	v_add_f32_e32 v184, v184, v186
	v_add_f32_e32 v185, v185, v187
	v_add_f32_e32 v208, v212, v210
	v_add_f32_e32 v209, v213, v217
	v_add_f32_e32 v240, v184, v185
	v_add_f32_e32 v241, v185, v184
	v_add_f32_e32 v212, v208, v209
	v_add_f32_e32 v213, v209, v208
	ds_bpermute_b32 v216, v235, v212
	ds_bpermute_b32 v184, v235, v240
	s_waitcnt lgkmcnt(1)
	v_add_f32_e32 v208, v212, v216
	s_waitcnt lgkmcnt(0)
	v_cndmask_b32_e64 v213, 0, v184, s[10:11]
	v_add_f32_e32 v208, v213, v208
	v_add_f32_e32 v245, v162, v208
	v_add_f32_e32 v246, v186, v185
	v_add_f32_e32 v247, v180, v245
	v_add_f32_e32 v182, v182, v245
	v_add_f32_e32 v180, v246, v247
	v_mul_f32_e32 v180, 0x3fb8aa3b, v180
	v_exp_f32_e32 v180, v180
	v_add_f32_e32 v182, v185, v182
	v_mul_f32_e32 v182, 0x3fb8aa3b, v182
	v_exp_f32_e32 v182, v182
	v_add_f32_e32 v176, v176, v178
	v_add_f32_e32 v177, v177, v179
	v_mov_b32_e32 v213, v180
	v_add_f32_e32 v180, v181, v245
	v_add_f32_e32 v242, v176, v177
	v_add_f32_e32 v243, v177, v176
	v_add_f32_e32 v180, v187, v180
	ds_bpermute_b32 v80, v235, v172
	ds_bpermute_b32 v176, v235, v242
	v_mul_f32_e32 v180, 0x3fb8aa3b, v180
	v_mov_b32_e32 v215, v182
	v_exp_f32_e32 v239, v180
	v_add_f32_e32 v180, v183, v245
	v_add_f32_e32 v182, v184, v216
	v_add_f32_e32 v183, v240, v212
	v_add_f32_e32 v180, 0, v180
	v_add_f32_e32 v181, v242, v183
	v_add_f32_e32 v181, v181, v216
	v_add_f32_e32 v181, v181, v184
	v_cndmask_b32_e64 v173, 0, v216, s[10:11]
	s_waitcnt lgkmcnt(1)
	v_cndmask_b32_e64 v208, 0, v80, s[10:11]
	v_mul_f32_e32 v180, 0x3fb8aa3b, v180
	s_waitcnt lgkmcnt(0)
	v_add_f32_e32 v181, v181, v176
	v_exp_f32_e32 v241, v180
	v_add_f32_e32 v180, v162, v173
	v_add_f32_e32 v173, v183, v216
	v_add_f32_e32 v181, v208, v181
	v_cndmask_b32_e64 v186, 0, v176, s[10:11]
	v_add_f32_e32 v173, v173, v184
	v_add_f32_e32 v185, v162, v181
	v_add_f32_e32 v173, v186, v173
	v_add_f32_e32 v164, v164, v185
	v_add_f32_e32 v186, v174, v81
	v_add_f32_e32 v187, v166, v185
	v_add_f32_e32 v81, v81, v164
	v_add_f32_e32 v164, v167, v185
	v_add_f32_e32 v165, v165, v185
	v_add_f32_e32 v166, v186, v187
	v_add_f32_e32 v164, v175, v164
	v_add_f32_e32 v165, 0, v165
	v_mul_f32_e32 v166, 0x3fb8aa3b, v166
	v_mul_f32_e32 v164, 0x3fb8aa3b, v164
	v_mul_f32_e32 v165, 0x3fb8aa3b, v165
	v_exp_f32_e32 v166, v166
	v_exp_f32_e32 v164, v164
	v_exp_f32_e32 v165, v165
	v_mov_b32_e32 v174, v166
	v_mov_b32_e32 v175, v164
	v_mov_b32_e32 v181, v165
	v_add_f32_e32 v165, v162, v173
	v_add_f32_e32 v166, v178, v177
	v_add_f32_e32 v167, v168, v165
	v_mul_f32_e32 v81, 0x3fb8aa3b, v81
	v_add_f32_e32 v164, v166, v167
	v_add_f32_e32 v166, v170, v165
	v_add_f32_e32 v167, v169, v165
	v_add_f32_e32 v165, v171, v165
	v_add_f32_e32 v166, v177, v166
	v_add_f32_e32 v167, v179, v167
	v_add_f32_e32 v165, 0, v165
	v_mul_f32_e32 v164, 0x3fb8aa3b, v164
	v_mul_f32_e32 v166, 0x3fb8aa3b, v166
	v_mul_f32_e32 v167, 0x3fb8aa3b, v167
	v_mul_f32_e32 v165, 0x3fb8aa3b, v165
	v_exp_f32_e32 v81, v81
	v_exp_f32_e32 v164, v164
	v_exp_f32_e32 v166, v166
	v_exp_f32_e32 v167, v167
	v_exp_f32_e32 v165, v165
	v_mov_b32_e32 v168, v164
	v_mov_b32_e32 v169, v165
	v_cvt_pk_bf16_f32 v164, v174, v81
	v_cvt_pk_bf16_f32 v165, v175, v181
	v_cvt_pk_bf16_f32 v166, v168, v166
	v_cvt_pk_bf16_f32 v167, v167, v169
	s_nop 0
	s_nop 0
	v_mfma_f32_32x32x16_bf16 v[48:63], v[146:149], v[164:167], v[48:63]
	v_add_f32_e64 v146, v180, v188
	v_add_f32_e64 v147, v210, v209
	v_add_f32_e32 v81, v146, v147
	v_mul_f32_e32 v81, 0x3fb8aa3b, v81
	v_exp_f32_e32 v81, v81
	v_mfma_f32_32x32x16_bf16 v[32:47], v[142:145], v[164:167], v[32:47]
	v_add_f32_e32 v143, v180, v190
	v_add_f32_e32 v144, v180, v189
	v_add_f32_e32 v143, v143, v209
	v_mul_f32_e32 v143, 0x3fb8aa3b, v143
	v_exp_f32_e32 v143, v143
	v_mfma_f32_32x32x16_bf16 v[16:31], v[138:141], v[164:167], v[16:31]
	v_add_f32_e32 v139, v180, v191
	v_add_f32_e32 v138, v144, v217
	v_add_f32_e32 v139, 0, v139
	v_mul_f32_e32 v138, 0x3fb8aa3b, v138
	v_mul_f32_e32 v139, 0x3fb8aa3b, v139
	v_exp_f32_e32 v138, v138
	v_exp_f32_e32 v139, v139
	v_mfma_f32_32x32x16_bf16 v[0:15], v[134:137], v[164:167], v[0:15]
	v_cvt_pk_bf16_f32 v134, v213, v215
	v_cvt_pk_bf16_f32 v135, v239, v241
	v_cvt_pk_bf16_f32 v136, v81, v143
	v_cvt_pk_bf16_f32 v137, v138, v139
	ds_read_b64_tr_b16 v[138:139], v207 offset:50240
	ds_read_b64_tr_b16 v[142:143], v207 offset:50304
	ds_read_b64_tr_b16 v[146:147], v207 offset:50368
	ds_read_b64_tr_b16 v[140:141], v207 offset:52800
	ds_read_b64_tr_b16 v[144:145], v207 offset:52864
	ds_read_b64_tr_b16 v[148:149], v207 offset:52928
	v_mfma_f32_32x32x16_bf16 v[48:63], v[130:133], v[134:137], v[48:63]
	v_mov_b32_e32 v130, v64
	v_mov_b32_e32 v131, v68
	v_mul_f32_e64 v132, v130, s68
	v_mul_f32_e64 v133, v131, s68
	v_mul_f32_e64 v64, |v132|, s54
	v_exp_f32_e32 v64, v64
	v_add_f32_e32 v80, v80, v176
	v_add_f32_e32 v81, v172, v242
	s_waitcnt lgkmcnt(2)
	v_mfma_f32_32x32x16_bf16 v[32:47], v[138:141], v[134:137], v[32:47]
	v_add_f32_e64 v80, v80, v182
	v_add_f32_e64 v81, v81, v183
	v_add_f32_e32 v64, 1.0, v64
	s_nop 1
	v_log_f32_e32 v138, v64
	v_min_f32_e32 v64, 0, v132
	s_waitcnt lgkmcnt(1)
	v_mfma_f32_32x32x16_bf16 v[16:31], v[142:145], v[134:137], v[16:31]
	v_mul_f32_e64 v143, |v133|, s54
	v_mul_f32_e32 v68, 0x3f317217, v138
	v_fma_f32 v132, v138, s86, -v68
	v_mov_b32_e32 v68, v65
	v_fmac_f32_e32 v132, 0x3377d1cf, v138
	v_fmac_f32_e32 v132, 0x3f317217, v138
	s_waitcnt lgkmcnt(0)
	v_mfma_f32_32x32x16_bf16 v[0:15], v[146:149], v[134:137], v[0:15]
	v_mul_f32_e64 v134, v68, s68
	v_mul_f32_e64 v135, v69, s68
	v_mul_f32_e64 v65, |v134|, s54
	v_exp_f32_e32 v65, v65
	v_mov_b32_e32 v137, v70
	v_exp_f32_e32 v143, v143
	v_min_f32_e32 v134, 0, v134
	v_add_f32_e32 v65, 1.0, v65
	v_add_f32_e32 v143, 1.0, v143
	s_nop 0
	v_log_f32_e32 v65, v65
	s_nop 0
	v_mul_f32_e32 v136, 0x3f317217, v65
	v_fma_f32 v140, v65, s86, -v136
	v_mov_b32_e32 v136, v66
	v_mul_f32_e32 v138, s68, v136
	v_mul_f32_e32 v139, s68, v137
	v_fmac_f32_e32 v140, 0x3377d1cf, v65
	v_mul_f32_e64 v66, |v138|, s54
	v_exp_f32_e32 v66, v66
	v_fmac_f32_e32 v140, 0x3f317217, v65
	v_min_f32_e32 v138, 0, v138
	v_add_f32_e32 v66, 1.0, v66
	v_mov_b32_e32 v65, v140
	s_nop 1
	v_log_f32_e32 v142, v66
	v_mov_b32_e32 v70, v67
	v_mul_f32_e32 v140, s68, v70
	v_mul_f32_e32 v141, s68, v71
	v_mul_f32_e64 v67, |v140|, s54
	v_exp_f32_e32 v67, v67
	v_mov_b32_e32 v66, v65
	v_mul_f32_e32 v65, 0x3f317217, v142
	v_fma_f32 v65, v142, s86, -v65
	v_fmac_f32_e32 v65, 0x3377d1cf, v142
	v_fmac_f32_e32 v65, 0x3f317217, v142
	v_add_f32_e32 v67, 1.0, v67
	v_min_f32_e32 v140, 0, v140
	s_nop 1
	v_log_f32_e32 v67, v67
	v_mov_b32_e32 v142, v65
	v_mul_f32_e32 v65, 0x3f317217, v67
	v_fma_f32 v65, v67, s86, -v65
	v_fmac_f32_e32 v65, 0x3377d1cf, v67
	v_fmac_f32_e32 v65, 0x3f317217, v67
	s_nop 1
	s_nop 0
	v_log_f32_e32 v143, v143
	v_mov_b32_e32 v144, v65
	v_min_f32_e32 v65, 0, v133
	v_mul_f32_e32 v133, 0x3f317217, v143
	v_fma_f32 v133, v143, s86, -v133
	v_fmac_f32_e32 v133, 0x3377d1cf, v143
	v_fmac_f32_e32 v133, 0x3f317217, v143
	s_nop 1
	v_sub_f32_e32 v64, v64, v132
	v_sub_f32_e32 v65, v65, v133
	v_mul_f32_e64 v132, |v135|, s54
	v_exp_f32_e32 v132, v132
	v_fma_f32 v130, -v130, s68, v64
	v_fma_f32 v131, -v131, s68, v65
	v_add_f32_e32 v67, 1.0, v132
	v_mov_b32_e32 v146, v130
	v_min_f32_e32 v135, 0, v135
	v_log_f32_e32 v67, v67
	v_mov_b32_e32 v147, v131
	v_mul_f32_e32 v132, 0x3f317217, v67
	v_fma_f32 v132, v67, s86, -v132
	v_fmac_f32_e32 v132, 0x3377d1cf, v67
	v_fmac_f32_e32 v132, 0x3f317217, v67
	s_nop 1
	v_mov_b32_e32 v67, v132
	v_mul_f32_e64 v132, |v139|, s54
	v_sub_f32_e32 v66, v134, v66
	v_sub_f32_e32 v67, v135, v67
	v_exp_f32_e32 v134, v132
	v_fma_f32 v68, -v68, s68, v66
	v_fma_f32 v69, -v69, s68, v67
	v_min_f32_e32 v139, 0, v139
	v_mov_b32_e32 v132, v68
	v_add_f32_e32 v68, 1.0, v134
	v_mov_b32_e32 v133, v69
	v_log_f32_e32 v68, v68
	s_nop 0
	v_mul_f32_e32 v69, 0x3f317217, v68
	v_fma_f32 v69, v68, s86, -v69
	v_fmac_f32_e32 v69, 0x3377d1cf, v68
	v_fmac_f32_e32 v69, 0x3f317217, v68
	s_nop 1
	v_sub_f32_e32 v68, v138, v142
	v_sub_f32_e32 v69, v139, v69
	v_fma_f32 v130, -v136, s68, v68
	v_fma_f32 v131, -v137, s68, v69
	v_mul_f32_e64 v136, |v141|, s54
	v_exp_f32_e32 v136, v136
	v_mov_b32_e32 v142, v130
	v_mov_b32_e32 v143, v131
	v_mul_f32_e32 v134, s68, v72
	v_mul_f32_e32 v135, s68, v73
	v_add_f32_e32 v130, 1.0, v136
	v_mul_f32_e64 v138, |v134|, s54
	v_exp_f32_e32 v138, v138
	v_log_f32_e32 v130, v130
	s_nop 0
	v_mul_f32_e32 v131, 0x3f317217, v130
	v_fma_f32 v131, v130, s86, -v131
	v_fmac_f32_e32 v131, 0x3377d1cf, v130
	v_fmac_f32_e32 v131, 0x3f317217, v130
	v_min_f32_e32 v134, 0, v134
	v_min_f32_e32 v141, 0, v141
	v_add_f32_e32 v136, 1.0, v138
	v_sub_f32_e32 v130, v140, v144
	v_sub_f32_e32 v131, v141, v131
	v_log_f32_e32 v136, v136
	v_mul_f32_e64 v138, |v135|, s54
	v_exp_f32_e32 v138, v138
	v_min_f32_e32 v135, 0, v135
	v_mul_f32_e32 v137, 0x3f317217, v136
	v_fma_f32 v137, v136, s86, -v137
	v_fmac_f32_e32 v137, 0x3377d1cf, v136
	v_fmac_f32_e32 v137, 0x3f317217, v136
	v_mov_b32_e32 v136, v137
	v_add_f32_e32 v137, 1.0, v138
	v_fma_f32 v70, -v70, s68, v130
	v_fma_f32 v71, -v71, s68, v131
	s_nop 0
	v_log_f32_e32 v137, v137
	v_mov_b32_e32 v136, v136
	v_mul_f32_e32 v138, 0x3f317217, v137
	v_fma_f32 v138, v137, s86, -v138
	v_fmac_f32_e32 v138, 0x3377d1cf, v137
	v_fmac_f32_e32 v138, 0x3f317217, v137
	s_nop 0
	v_sub_f32_e32 v134, v134, v136
	v_sub_f32_e32 v135, v135, v138
	v_mul_f32_e32 v136, s68, v74
	v_mul_f32_e32 v137, s68, v75
	v_mul_f32_e64 v139, |v136|, s54
	v_exp_f32_e32 v139, v139
	v_mul_f32_e64 v140, |v137|, s54
	v_exp_f32_e32 v140, v140
	v_add_f32_e32 v138, 1.0, v139
	v_min_f32_e32 v136, 0, v136
	v_min_f32_e32 v137, 0, v137
	v_log_f32_e32 v138, v138
	v_fma_f32 v72, -v72, s68, v134
	v_fma_f32 v73, -v73, s68, v135
	v_mul_f32_e32 v139, 0x3f317217, v138
	v_fma_f32 v139, v138, s86, -v139
	v_fmac_f32_e32 v139, 0x3377d1cf, v138
	v_fmac_f32_e32 v139, 0x3f317217, v138
	v_mov_b32_e32 v138, v139
	v_add_f32_e32 v139, 1.0, v140
	s_nop 1
	v_log_f32_e32 v139, v139
	v_mov_b32_e32 v138, v138
	v_mul_f32_e32 v140, 0x3f317217, v139
	v_fma_f32 v140, v139, s86, -v140
	v_fmac_f32_e32 v140, 0x3377d1cf, v139
	v_fmac_f32_e32 v140, 0x3f317217, v139
	s_nop 1
	v_mov_b32_e32 v139, v140
	v_add_f32_e32 v140, v142, v70
	v_add_f32_e32 v141, v143, v71
	v_mov_b32_e32 v142, v76
	v_mov_b32_e32 v143, v78
	v_mul_f32_e32 v144, s68, v142
	v_mul_f32_e32 v145, s68, v143
	v_sub_f32_e32 v136, v136, v138
	v_sub_f32_e32 v137, v137, v139
	v_mul_f32_e64 v76, |v144|, s54
	v_exp_f32_e32 v78, v76
	v_fma_f32 v74, -v74, s68, v136
	v_fma_f32 v75, -v75, s68, v137
	v_mov_b32_e32 v138, v74
	v_mul_f32_e64 v149, |v145|, s54
	v_mov_b32_e32 v139, v75
	v_add_f32_e32 v74, v146, v132
	v_add_f32_e32 v75, v147, v133
	v_exp_f32_e32 v149, v149
	v_add_f32_e32 v146, v74, v140
	v_add_f32_e32 v147, v75, v141
	v_add_f32_e32 v74, 1.0, v78
	ds_bpermute_b32 v148, v235, v147
	ds_bpermute_b32 v76, v235, v146
	v_log_f32_e32 v75, v74
	s_nop 0
	v_mul_f32_e32 v78, 0x3f317217, v75
	v_add_f32_e32 v164, v72, v73
	v_add_f32_e32 v165, v73, v75
	v_min_f32_e32 v74, 0, v144
	v_fma_f32 v144, v75, s86, -v78
	v_mov_b32_e32 v78, v77
	v_mul_f32_e32 v166, s68, v78
	v_mul_f32_e32 v167, s68, v79
	v_fmac_f32_e32 v144, 0x3377d1cf, v75
	v_mul_f32_e64 v77, |v166|, s54
	v_exp_f32_e32 v77, v77
	v_fmac_f32_e32 v144, 0x3f317217, v75
	v_min_f32_e32 v166, 0, v166
	v_add_f32_e32 v77, 1.0, v77
	v_log_f32_e32 v77, v77
	v_mov_b32_e32 v144, v144
	v_mul_f32_e32 v75, 0x3f317217, v77
	v_fma_f32 v75, v77, s86, -v75
	v_fmac_f32_e32 v75, 0x3377d1cf, v77
	v_fmac_f32_e32 v75, 0x3f317217, v77
	s_nop 1
	v_mov_b32_e32 v168, v75
	v_add_f32_e32 v75, 1.0, v149
	s_nop 0
	v_log_f32_e32 v77, v75
	v_min_f32_e32 v75, 0, v145
	v_mul_f32_e32 v145, 0x3f317217, v77
	v_fma_f32 v145, v77, s86, -v145
	v_fmac_f32_e32 v145, 0x3377d1cf, v77
	v_fmac_f32_e32 v145, 0x3f317217, v77
	s_nop 1
	v_mov_b32_e32 v145, v145
	v_mul_f32_e64 v77, |v167|, s54
	v_exp_f32_e32 v77, v77
	v_sub_f32_e32 v74, v74, v144
	v_sub_f32_e32 v75, v75, v145
	v_min_f32_e32 v167, 0, v167
	v_add_f32_e32 v77, 1.0, v77
	v_log_f32_e32 v77, v77
	v_fma_f32 v142, -v142, s68, v74
	v_fma_f32 v143, -v143, s68, v75
	v_mul_f32_e32 v144, 0x3f317217, v77
	v_fma_f32 v144, v77, s86, -v144
	v_fmac_f32_e32 v144, 0x3377d1cf, v77
	v_fmac_f32_e32 v144, 0x3f317217, v77
	v_mov_b32_e32 v169, v144
	v_sub_f32_e32 v144, v166, v168
	v_sub_f32_e32 v145, v167, v169
	v_fma_f32 v78, -v78, s68, v144
	v_fma_f32 v79, -v79, s68, v145
	v_mov_b32_e32 v167, v79
	v_mov_b32_e32 v168, v132
	v_mov_b32_e32 v166, v78
	v_add_f32_e32 v142, v142, v166
	v_add_f32_e32 v143, v143, v167
	v_add_f32_e32 v170, v138, v139
	v_add_f32_e32 v171, v139, v133
	v_add_f32_e32 v164, v164, v170
	v_add_f32_e32 v165, v142, v143
	ds_bpermute_b32 v149, v235, v165
	ds_bpermute_b32 v77, v235, v164
	v_add_f32_e32 v78, v146, v146
	v_add_f32_e32 v79, v146, v147
	v_mov_b32_e32 v169, v64
	v_mov_b32_e32 v64, v133
	v_add_f32_e32 v132, v164, v165
	v_add_f32_e32 v133, v165, v164
	s_waitcnt lgkmcnt(1)
	v_add_f32_e32 v142, v165, v149
	s_waitcnt lgkmcnt(0)
	v_cndmask_b32_e64 v146, 0, v77, s[10:11]
	v_add_f32_e32 v142, v146, v142
	v_add_f32_e32 v146, v132, v149
	v_add_f32_e32 v147, v147, v132
	v_add_f32_e32 v146, v146, v77
	v_cndmask_b32_e64 v163, 0, v148, s[10:11]
	v_add_f32_e32 v147, v147, v149
	v_add_f32_e32 v146, v163, v146
	v_add_f32_e32 v147, v147, v77
	v_cndmask_b32_e64 v163, 0, v76, s[10:11]
	v_add_f32_e32 v76, v76, v148
	v_add_f32_e32 v77, v77, v149
	v_mov_b32_e32 v78, v80
	v_add_f32_e32 v147, v147, v148
	v_add_f32_e32 v77, v76, v77
	v_add_f32_e32 v76, v76, v76
	v_pk_mov_b32 v[80:81], v[80:81], v[132:133] op_sel:[1,0]
	v_add_f32_e32 v147, v163, v147
	v_add_f32_e32 v78, v78, v80
	v_add_f32_e32 v79, v79, v81
	v_mov_b32_e32 v163, v77
	v_add_f32_e32 v80, v162, v78
	v_add_f32_e32 v81, v163, v79
	v_add_f32_e32 v77, v80, v147
	v_add_f32_e32 v78, v168, v140
	v_add_f32_e32 v79, v169, v77
	v_add_f32_e32 v68, v68, v77
	v_add_f32_e32 v76, v78, v79
	v_mul_f32_e32 v76, 0x3fb8aa3b, v76
	v_exp_f32_e32 v76, v76
	v_add_f32_e32 v66, v66, v77
	v_add_f32_e32 v68, v70, v68
	v_add_f32_e32 v70, v130, v77
	v_mov_b32_e32 v78, v76
	v_add_f32_e32 v77, v80, v146
	v_add_f32_e32 v66, v140, v66
	v_add_f32_e32 v64, v64, v141
	v_add_f32_e32 v65, v65, v77
	v_mul_f32_e32 v66, 0x3fb8aa3b, v66
	v_add_f32_e32 v64, v64, v65
	v_add_f32_e32 v65, v67, v77
	v_exp_f32_e32 v66, v66
	v_add_f32_e32 v65, v141, v65
	v_mul_f32_e32 v64, 0x3fb8aa3b, v64
	v_mul_f32_e32 v65, 0x3fb8aa3b, v65
	v_exp_f32_e32 v64, v64
	v_exp_f32_e32 v65, v65
	v_mov_b32_e32 v79, v66
	v_add_f32_e32 v66, v69, v77
	v_add_f32_e32 v66, v71, v66
	v_mul_f32_e32 v66, 0x3fb8aa3b, v66
	v_mov_b32_e32 v71, v64
	v_mov_b32_e32 v76, v65
	v_add_f32_e32 v171, v80, v142
	v_pk_mov_b32 v[64:65], v[72:73], v[134:135] op_sel:[1,0]
	v_exp_f32_e32 v66, v66
	v_add_f32_e32 v67, v131, v77
	v_add_f32_e32 v64, v64, v170
	v_add_f32_e32 v65, v65, v171
	v_add_f32_e32 v67, 0, v67
	v_add_f32_e32 v64, v64, v65
	v_add_f32_e32 v65, v135, v171
	v_mul_f32_e32 v67, 0x3fb8aa3b, v67
	v_mul_f32_e32 v64, 0x3fb8aa3b, v64
	v_add_f32_e32 v65, v170, v65
	v_exp_f32_e32 v67, v67
	v_exp_f32_e32 v64, v64
	v_mul_f32_e32 v65, 0x3fb8aa3b, v65
	v_add_f32_e32 v70, 0, v70
	v_mov_b32_e32 v77, v66
	v_exp_f32_e32 v140, v65
	v_add_f32_e32 v65, v136, v171
	v_add_f32_e32 v66, v137, v171
	v_mul_f32_e32 v68, 0x3fb8aa3b, v68
	v_mul_f32_e32 v70, 0x3fb8aa3b, v70
	v_add_f32_e32 v65, v139, v65
	v_add_f32_e32 v66, 0, v66
	v_exp_f32_e32 v68, v68
	v_exp_f32_e32 v70, v70
	v_mul_f32_e32 v65, 0x3fb8aa3b, v65
	v_mul_f32_e32 v66, 0x3fb8aa3b, v66
	v_mov_b32_e32 v131, v67
	v_exp_f32_e32 v139, v66
	v_exp_f32_e32 v141, v65
	v_mov_b32_e32 v146, v64
	ds_read_b64_tr_b16 v[64:65], v207 offset:34816
	ds_read_b64_tr_b16 v[66:67], v207 offset:37376
	v_cndmask_b32_e64 v138, 0, v149, s[10:11]
	v_add_f32_e32 v72, v80, v138
	v_mov_b32_e32 v142, v74
	v_mov_b32_e32 v130, v68
	v_add_f32_e32 v68, v72, v142
	v_add_f32_e32 v69, v166, v143
	v_mov_b32_e32 v74, v139
	v_add_f32_e32 v73, v68, v69
	v_cvt_pk_bf16_f32 v68, v78, v79
	v_cvt_pk_bf16_f32 v69, v130, v70
	v_cvt_pk_bf16_f32 v70, v71, v76
	v_cvt_pk_bf16_f32 v71, v77, v131
	ds_read_b64_tr_b16 v[76:77], v207 offset:34880
	ds_read_b64_tr_b16 v[130:131], v207 offset:34944
	ds_read_b64_tr_b16 v[134:135], v207 offset:35008
	ds_read_b64_tr_b16 v[78:79], v207 offset:37440
	ds_read_b64_tr_b16 v[132:133], v207 offset:37504
	ds_read_b64_tr_b16 v[136:137], v207 offset:37568
	s_waitcnt lgkmcnt(6)
	v_mfma_f32_32x32x16_bf16 v[48:63], v[64:67], v[68:71], v[48:63]
	v_mul_f32_e32 v64, 0x3fb8aa3b, v73
	v_exp_f32_e32 v64, v64
	v_add_f32_e32 v65, v72, v75
	v_add_f32_e32 v65, v65, v167
	v_mul_f32_e32 v65, 0x3fb8aa3b, v65
	v_mov_b32_e32 v139, v64
	v_add_f32_e32 v64, v72, v144
	v_exp_f32_e32 v75, v65
	v_add_f32_e32 v65, v72, v145
	v_add_f32_e32 v64, v64, v143
	v_add_f32_e32 v65, 0, v65
	v_mul_f32_e32 v64, 0x3fb8aa3b, v64
	v_mul_f32_e32 v65, 0x3fb8aa3b, v65
	v_exp_f32_e32 v64, v64
	v_exp_f32_e32 v72, v65
	s_waitcnt lgkmcnt(2)
	v_mfma_f32_32x32x16_bf16 v[32:47], v[76:79], v[68:71], v[32:47]
	v_mov_b32_e32 v138, v141
	v_mov_b32_e32 v76, v64
	ds_read_b64_tr_b16 v[64:65], v207 offset:39936
	ds_read_b64_tr_b16 v[66:67], v207 offset:42496
	v_add_f32_e32 v162, v80, v81
	s_mov_b32 s14, 0xc2480000
	s_waitcnt lgkmcnt(3)
	v_mfma_f32_32x32x16_bf16 v[16:31], v[130:133], v[68:71], v[16:31]
	v_cmp_gt_f32_e32 vcc, s14, v162
	s_cmp_eq_u64 vcc, exec
	s_cselect_b64 s[14:15], -1, 0
	s_waitcnt lgkmcnt(2)
	v_mfma_f32_32x32x16_bf16 v[0:15], v[134:137], v[68:71], v[0:15]
	v_cvt_pk_bf16_f32 v68, v146, v140
	v_cvt_pk_bf16_f32 v69, v138, v74
	v_cvt_pk_bf16_f32 v70, v139, v76
	v_cvt_pk_bf16_f32 v71, v75, v72
	ds_read_b64_tr_b16 v[72:73], v207 offset:40000
	ds_read_b64_tr_b16 v[76:77], v207 offset:40064
	ds_read_b64_tr_b16 v[130:131], v207 offset:40128
	ds_read_b64_tr_b16 v[74:75], v207 offset:42560
	ds_read_b64_tr_b16 v[78:79], v207 offset:42624
	ds_read_b64_tr_b16 v[132:133], v207 offset:42688
	s_waitcnt lgkmcnt(6)
	v_mfma_f32_32x32x16_bf16 v[48:63], v[64:67], v[68:71], v[48:63]
	s_waitcnt lgkmcnt(2)
	v_mfma_f32_32x32x16_bf16 v[32:47], v[72:75], v[68:71], v[32:47]
	s_waitcnt lgkmcnt(1)
	v_mfma_f32_32x32x16_bf16 v[16:31], v[76:79], v[68:71], v[16:31]
	s_waitcnt lgkmcnt(0)
	v_mfma_f32_32x32x16_bf16 v[0:15], v[130:133], v[68:71], v[0:15]
	s_branch .LBB0_467
.Lsb_near:
	v_add3_u32 v130, s18, v192, v205
	ds_read_b128 v[132:135], v130 offset:8704
	ds_read_b128 v[136:139], v130 offset:8736
	ds_read_b128 v[140:143], v130 offset:8768
	ds_read_b128 v[144:147], v130 offset:8800
	ds_read_b128 v[164:167], v130 offset:8832
	ds_read_b128 v[168:171], v130 offset:8864
	ds_read_b128 v[172:175], v130 offset:8896
	ds_read_b128 v[176:179], v130 offset:8928
	ds_read_b128 v[208:211], v130 offset:224
	v_or_b32_e32 v163, s23, v200
	v_add3_u32 v207, s22, v204, v206
	s_waitcnt lgkmcnt(8)
	v_mfma_f32_32x32x16_bf16 v[66:81], v[132:135], v[82:85], 0
	s_waitcnt lgkmcnt(7)
	v_mfma_f32_32x32x16_bf16 v[66:81], v[136:139], v[86:89], v[66:81]
	s_waitcnt lgkmcnt(6)
	v_mfma_f32_32x32x16_bf16 v[66:81], v[140:143], v[90:93], v[66:81]
	s_waitcnt lgkmcnt(5)
	v_mfma_f32_32x32x16_bf16 v[66:81], v[144:147], v[94:97], v[66:81]
	s_waitcnt lgkmcnt(4)
	v_mfma_f32_32x32x16_bf16 v[66:81], v[164:167], v[98:101], v[66:81]
	s_waitcnt lgkmcnt(3)
	v_mfma_f32_32x32x16_bf16 v[66:81], v[168:171], v[102:105], v[66:81]
	s_waitcnt lgkmcnt(2)
	v_mfma_f32_32x32x16_bf16 v[66:81], v[172:175], v[106:109], v[66:81]
	s_waitcnt lgkmcnt(1)
	v_mfma_f32_32x32x16_bf16 v[66:81], v[176:179], v[110:113], v[66:81]
	s_nop 11
	v_mov_b32_e32 v64, v66
	v_mov_b32_e32 v65, v68
	v_mov_b32_e32 v68, v67
	v_mul_f32_e32 v132, s68, v64
	v_mul_f32_e32 v133, s68, v65
	v_mov_b32_e32 v66, v70
	v_mul_f32_e32 v134, s68, v68
	v_mul_f32_e32 v135, s68, v69
	v_mul_f32_e64 v70, |v132|, s54
	v_mov_b32_e32 v67, v72
	v_mul_f32_e64 v72, |v134|, s54
	v_exp_f32_e32 v70, v70
	v_mul_f32_e64 v131, |v133|, s54
	v_exp_f32_e32 v72, v72
	v_mul_f32_e64 v138, |v135|, s54
	v_exp_f32_e32 v131, v131
	v_mul_f32_e32 v136, s68, v66
	v_mul_f32_e32 v137, s68, v67
	v_exp_f32_e32 v138, v138
	v_mul_f32_e64 v139, |v136|, s54
	v_add_f32_e32 v70, 1.0, v70
	v_exp_f32_e32 v139, v139
	v_add_f32_e32 v72, 1.0, v72
	v_add_f32_e32 v131, 1.0, v131
	v_add_f32_e32 v138, 1.0, v138
	v_log_f32_e32 v70, v70
	v_add_f32_e32 v139, 1.0, v139
	v_log_f32_e32 v72, v72
	v_log_f32_e32 v131, v131
	v_log_f32_e32 v138, v138
	v_mov_b32_e32 v142, v139
	v_mul_f32_e32 v139, 0x3f317217, v70
	v_mul_f32_e32 v140, 0x3f317217, v72
	v_fma_f32 v139, v70, s86, -v139
	v_mul_f32_e32 v141, 0x3f317217, v131
	v_fma_f32 v140, v72, s86, -v140
	v_fmac_f32_e32 v139, 0x3377d1cf, v70
	v_mul_f32_e32 v143, 0x3f317217, v138
	v_fma_f32 v141, v131, s86, -v141
	v_fmac_f32_e32 v140, 0x3377d1cf, v72
	v_fmac_f32_e32 v139, 0x3f317217, v70
	v_fma_f32 v143, v138, s86, -v143
	v_fmac_f32_e32 v141, 0x3377d1cf, v131
	v_fmac_f32_e32 v140, 0x3f317217, v72
	v_fmac_f32_e32 v143, 0x3377d1cf, v138
	v_fmac_f32_e32 v141, 0x3f317217, v131
	v_fmac_f32_e32 v143, 0x3f317217, v138
	v_min_f32_e32 v132, 0, v132
	v_min_f32_e32 v133, 0, v133
	v_sub_f32_e32 v166, v132, v139
	v_sub_f32_e32 v167, v133, v141
	v_fma_f32 v174, -v64, s68, v166
	v_fma_f32 v175, -v65, s68, v167
	v_log_f32_e32 v65, v142
	v_min_f32_e32 v134, 0, v134
	v_min_f32_e32 v135, 0, v135
	v_sub_f32_e32 v164, v134, v140
	v_sub_f32_e32 v165, v135, v143
	v_mov_b32_e32 v72, v71
	v_fma_f32 v172, -v68, s68, v164
	v_fma_f32 v173, -v69, s68, v165
	v_mul_f32_e32 v68, 0x3f317217, v65
	v_fma_f32 v70, v65, s86, -v68
	v_mul_f32_e32 v68, s68, v72
	v_mul_f32_e32 v69, s68, v73
	v_fmac_f32_e32 v70, 0x3377d1cf, v65
	v_mul_f32_e64 v71, |v68|, s54
	v_exp_f32_e32 v71, v71
	v_fmac_f32_e32 v70, 0x3f317217, v65
	v_mul_f32_e64 v131, |v137|, s54
	v_exp_f32_e32 v131, v131
	v_mov_b32_e32 v65, v70
	v_add_f32_e32 v70, 1.0, v71
	v_mul_f32_e64 v133, |v69|, s54
	v_exp_f32_e32 v133, v133
	v_log_f32_e32 v71, v70
	v_mov_b32_e32 v70, v65
	v_min_f32_e32 v64, 0, v136
	v_mul_f32_e32 v65, 0x3f317217, v71
	v_fma_f32 v65, v71, s86, -v65
	v_fmac_f32_e32 v65, 0x3377d1cf, v71
	v_fmac_f32_e32 v65, 0x3f317217, v71
	v_min_f32_e32 v68, 0, v68
	v_min_f32_e32 v69, 0, v69
	v_add_f32_e32 v71, 1.0, v131
	v_mov_b32_e32 v140, v78
	v_mov_b32_e32 v141, v80
	v_log_f32_e32 v71, v71
	v_mov_b32_e32 v132, v65
	v_min_f32_e32 v65, 0, v137
	v_mul_f32_e32 v131, 0x3f317217, v71
	v_fma_f32 v131, v71, s86, -v131
	v_fmac_f32_e32 v131, 0x3377d1cf, v71
	v_fmac_f32_e32 v131, 0x3f317217, v71
	v_mul_f32_e32 v142, s68, v140
	v_mul_f32_e32 v143, s68, v141
	v_mov_b32_e32 v80, v79
	v_mov_b32_e32 v71, v131
	v_add_f32_e32 v131, 1.0, v133
	v_sub_f32_e32 v168, v64, v70
	v_sub_f32_e32 v169, v65, v71
	v_log_f32_e32 v131, v131
	v_fma_f32 v176, -v66, s68, v168
	v_fma_f32 v177, -v67, s68, v169
	v_mul_f32_e32 v144, s68, v80
	v_mul_f32_e32 v145, s68, v81
	v_mul_f32_e32 v64, 0x3f317217, v131
	v_fma_f32 v70, v131, s86, -v64
	v_mov_b32_e32 v64, v74
	v_mul_f32_e32 v66, s68, v64
	v_mul_f32_e32 v67, s68, v76
	v_fmac_f32_e32 v70, 0x3377d1cf, v131
	v_mul_f32_e64 v71, |v66|, s54
	v_exp_f32_e32 v71, v71
	v_fmac_f32_e32 v70, 0x3f317217, v131
	v_min_f32_e32 v66, 0, v66
	v_mov_b32_e32 v133, v70
	v_add_f32_e32 v70, 1.0, v71
	v_sub_f32_e32 v170, v68, v132
	v_sub_f32_e32 v171, v69, v133
	ds_read_b128 v[132:135], v130 offset:32
	v_log_f32_e32 v70, v70
	v_fma_f32 v178, -v72, s68, v170
	v_fma_f32 v179, -v73, s68, v171
	v_mul_f32_e64 v73, |v67|, s54
	v_exp_f32_e32 v73, v73
	v_mul_f32_e32 v68, 0x3f317217, v70
	v_fma_f32 v71, v70, s86, -v68
	v_mul_f32_e32 v68, s68, v75
	v_mul_f32_e32 v69, s68, v77
	v_fmac_f32_e32 v71, 0x3377d1cf, v70
	v_mul_f32_e64 v72, |v68|, s54
	v_exp_f32_e32 v72, v72
	v_fmac_f32_e32 v71, 0x3f317217, v70
	v_mul_f32_e64 v74, |v69|, s54
	v_exp_f32_e32 v74, v74
	v_mov_b32_e32 v70, v71
	v_add_f32_e32 v71, 1.0, v72
	v_min_f32_e32 v67, 0, v67
	v_min_f32_e32 v68, 0, v68
	v_log_f32_e32 v71, v71
	v_mov_b32_e32 v70, v70
	v_min_f32_e32 v69, 0, v69
	v_mul_f32_e32 v72, 0x3f317217, v71
	v_fma_f32 v72, v71, s86, -v72
	v_fmac_f32_e32 v72, 0x3377d1cf, v71
	v_fmac_f32_e32 v72, 0x3f317217, v71
	s_nop 1
	v_mov_b32_e32 v71, v72
	v_add_f32_e32 v72, 1.0, v73
	s_nop 1
	v_log_f32_e32 v73, v72
	v_mov_b32_e32 v72, v71
	v_mul_f32_e32 v71, 0x3f317217, v73
	v_fma_f32 v71, v73, s86, -v71
	v_fmac_f32_e32 v71, 0x3377d1cf, v73
	v_fmac_f32_e32 v71, 0x3f317217, v73
	s_nop 1
	v_add_f32_e32 v73, 1.0, v74
	v_sub_f32_e32 v180, v66, v70
	v_sub_f32_e32 v181, v67, v71
	v_mul_f32_e64 v70, |v143|, s54
	v_log_f32_e32 v73, v73
	v_fma_f32 v184, -v64, s68, v180
	v_fma_f32 v185, -v76, s68, v181
	v_mul_f32_e64 v65, |v142|, s54
	v_exp_f32_e32 v65, v65
	v_mul_f32_e32 v64, 0x3f317217, v73
	v_fma_f32 v64, v73, s86, -v64
	v_fmac_f32_e32 v64, 0x3377d1cf, v73
	v_fmac_f32_e32 v64, 0x3f317217, v73
	v_exp_f32_e32 v131, v70
	v_mov_b32_e32 v73, v64
	v_add_f32_e32 v64, 1.0, v65
	v_mul_f32_e64 v66, |v144|, s54
	v_exp_f32_e32 v66, v66
	v_log_f32_e32 v64, v64
	v_sub_f32_e32 v182, v68, v72
	v_sub_f32_e32 v183, v69, v73
	v_add_f32_e32 v131, 1.0, v131
	v_fma_f32 v186, -v75, s68, v182
	v_fma_f32 v187, -v77, s68, v183
	v_mul_f32_e32 v65, 0x3f317217, v64
	v_fma_f32 v65, v64, s86, -v65
	v_fmac_f32_e32 v65, 0x3377d1cf, v64
	v_fmac_f32_e32 v65, 0x3f317217, v64
	v_min_f32_e32 v142, 0, v142
	v_min_f32_e32 v143, 0, v143
	v_mov_b32_e32 v64, v65
	v_add_f32_e32 v65, 1.0, v66
	v_min_f32_e32 v144, 0, v144
	v_log_f32_e32 v68, v65
	v_mov_b32_e32 v146, v64
	ds_read_b128 v[64:67], v130
	v_mul_f32_e32 v69, 0x3f317217, v68
	v_fma_f32 v69, v68, s86, -v69
	v_fmac_f32_e32 v69, 0x3377d1cf, v68
	v_fmac_f32_e32 v69, 0x3f317217, v68
	s_nop 0
	v_mov_b32_e32 v147, v69
	s_waitcnt lgkmcnt(0)
	v_mfma_f32_32x32x16_bf16 v[64:79], v[64:67], v[82:85], 0
	v_mov_b32_e32 v148, v147
	s_nop 0
	ds_read_b128 v[136:139], v130 offset:64
	v_log_f32_e32 v131, v131
	v_mfma_f32_32x32x16_bf16 v[64:79], v[132:135], v[86:89], v[64:79]
	v_mul_f32_e32 v132, 0x3f317217, v131
	v_fma_f32 v147, v131, s86, -v132
	ds_read_b128 v[132:135], v130 offset:96
	v_fmac_f32_e32 v147, 0x3377d1cf, v131
	v_fmac_f32_e32 v147, 0x3f317217, v131
	s_waitcnt lgkmcnt(1)
	v_mfma_f32_32x32x16_bf16 v[64:79], v[136:139], v[90:93], v[64:79]
	v_mul_f32_e64 v137, |v145|, s54
	v_exp_f32_e32 v149, v137
	ds_read_b128 v[136:139], v130 offset:128
	s_waitcnt lgkmcnt(1)
	v_mfma_f32_32x32x16_bf16 v[64:79], v[132:135], v[94:97], v[64:79]
	v_add_f32_e32 v131, 1.0, v149
	v_add_f32_e64 v188, v142, -v146
	v_add_f32_e64 v189, v143, -v147
	v_min_f32_e32 v145, 0, v145
	ds_read_b128 v[132:135], v130 offset:160
	s_waitcnt lgkmcnt(1)
	v_mfma_f32_32x32x16_bf16 v[64:79], v[136:139], v[98:101], v[64:79]
	v_log_f32_e32 v131, v131
	v_fma_f32 v212, -v140, s68, v188
	v_fma_f32 v213, -v141, s68, v189
	v_mul_f32_e32 v136, 0x3f317217, v131
	v_fma_f32 v140, v131, s86, -v136
	ds_read_b128 v[136:139], v130 offset:192
	s_waitcnt lgkmcnt(1)
	v_mfma_f32_32x32x16_bf16 v[64:79], v[132:135], v[102:105], v[64:79]
	v_fmac_f32_e32 v140, 0x3377d1cf, v131
	v_fmac_f32_e32 v140, 0x3f317217, v131
	s_nop 0
	s_waitcnt lgkmcnt(0)
	v_mfma_f32_32x32x16_bf16 v[64:79], v[136:139], v[106:109], v[64:79]
	v_add_f32_e64 v190, v144, -v148
	v_add_f32_e64 v191, v145, -v140
	ds_read_b64_tr_b16 v[146:147], v207 offset:45056
	ds_read_b64_tr_b16 v[142:143], v207 offset:45120
	ds_read_b64_tr_b16 v[138:139], v207 offset:45184
	ds_read_b64_tr_b16 v[134:135], v207 offset:45248
	ds_read_b64_tr_b16 v[148:149], v207 offset:47616
	ds_read_b64_tr_b16 v[144:145], v207 offset:47680
	ds_read_b64_tr_b16 v[140:141], v207 offset:47744
	ds_read_b64_tr_b16 v[136:137], v207 offset:47808
	ds_read_b64_tr_b16 v[130:131], v207 offset:50176
	ds_read_b64_tr_b16 v[132:133], v207 offset:52736
	v_fma_f32 v216, -v80, s68, v190
	v_fma_f32 v217, -v81, s68, v191
	v_or_b32_e32 v80, 34, v163
	v_cmp_lt_i32_e64 s[26:27], v80, v153
	v_mfma_f32_32x32x16_bf16 v[64:79], v[208:211], v[110:113], v[64:79]
	v_or_b32_e32 v208, 32, v163
	v_cmp_lt_i32_e64 s[30:31], v208, v152
	v_or_b32_e32 v208, 33, v163
	v_cmp_lt_i32_e64 s[40:41], v208, v152
	v_cndmask_b32_e64 v80, 0, v174, s[30:31]
	v_or_b32_e32 v174, 35, v163
	v_cmp_lt_i32_e64 s[38:39], v174, v153
	v_cndmask_b32_e64 v81, 0, v175, s[26:27]
	v_cndmask_b32_e64 v174, 0, v172, s[40:41]
	v_cndmask_b32_e64 v175, 0, v173, s[38:39]
	v_add_f32_e32 v80, v80, v174
	v_add_f32_e32 v81, v81, v175
	v_or_b32_e32 v208, 40, v163
	v_add_f32_e32 v172, v80, v81
	v_add_f32_e32 v173, v81, v80
	v_cmp_lt_i32_e64 s[22:23], v208, v152
	v_or_b32_e32 v173, 42, v163
	v_cmp_lt_i32_e64 s[18:19], v173, v153
	v_or_b32_e32 v173, 43, v163
	v_or_b32_e32 v208, 41, v163
	v_cmp_lt_i32_e64 s[28:29], v173, v153
	v_or_b32_e32 v173, 50, v163
	v_cmp_lt_i32_e64 s[34:35], v208, v152
	v_or_b32_e32 v208, 48, v163
	v_cmp_lt_i32_e32 vcc, v173, v153
	v_or_b32_e32 v173, 51, v163
	v_cmp_lt_i32_e64 s[42:43], v208, v152
	v_or_b32_e32 v208, 49, v163
	v_cmp_lt_i32_e64 s[16:17], v173, v153
	v_or_b32_e32 v173, 58, v163
	v_cmp_lt_i32_e64 s[44:45], v208, v152
	v_or_b32_e32 v208, 56, v163
	v_cmp_lt_i32_e64 s[14:15], v173, v153
	v_or_b32_e32 v173, 59, v163
	v_or_b32_e32 v210, 57, v163
	v_cmp_lt_i32_e64 s[36:37], v208, v152
	v_cmp_lt_i32_e64 s[20:21], v173, v153
	v_cmp_lt_i32_e64 s[24:25], v210, v152
	v_cndmask_b32_e32 v185, 0, v185, vcc
	v_cndmask_b32_e64 v184, 0, v184, s[42:43]
	v_cndmask_b32_e64 v187, 0, v187, s[16:17]
	v_cndmask_b32_e64 v186, 0, v186, s[44:45]
	v_cndmask_b32_e64 v209, 0, v213, s[14:15]
	v_cndmask_b32_e64 v208, 0, v212, s[36:37]
	v_cndmask_b32_e64 v211, 0, v217, s[20:21]
	v_cndmask_b32_e64 v210, 0, v216, s[24:25]
	v_add_f32_e32 v184, v184, v186
	v_add_f32_e32 v185, v185, v187
	v_add_f32_e32 v208, v208, v210
	v_add_f32_e32 v209, v209, v211
	v_add_f32_e32 v240, v184, v185
	v_add_f32_e32 v241, v185, v184
	v_add_f32_e32 v212, v208, v209
	v_add_f32_e32 v213, v209, v208
	ds_bpermute_b32 v216, v235, v212
	ds_bpermute_b32 v184, v235, v240
	v_cndmask_b32_e64 v177, 0, v177, s[18:19]
	s_waitcnt lgkmcnt(1)
	v_add_f32_e32 v208, v212, v216
	s_waitcnt lgkmcnt(0)
	v_cndmask_b32_e64 v213, 0, v184, s[10:11]
	v_add_f32_e32 v208, v213, v208
	v_add_f32_e32 v245, v162, v208
	v_add_f32_e32 v246, v186, v185
	v_add_f32_e32 v247, v180, v245
	v_add_f32_e32 v182, v182, v245
	v_add_f32_e32 v180, v246, v247
	v_mul_f32_e32 v180, 0x3fb8aa3b, v180
	v_exp_f32_e32 v180, v180
	v_add_f32_e32 v182, v185, v182
	v_mul_f32_e32 v182, 0x3fb8aa3b, v182
	v_cndmask_b32_e64 v176, 0, v176, s[22:23]
	v_cndmask_b32_e64 v179, 0, v179, s[28:29]
	v_cndmask_b32_e64 v178, 0, v178, s[34:35]
	v_exp_f32_e32 v182, v182
	v_add_f32_e32 v176, v176, v178
	v_add_f32_e32 v177, v177, v179
	v_cndmask_b32_e64 v213, 0, v180, s[42:43]
	v_add_f32_e32 v180, v181, v245
	v_add_f32_e32 v242, v176, v177
	v_add_f32_e32 v243, v177, v176
	v_add_f32_e32 v180, v187, v180
	ds_bpermute_b32 v80, v235, v172
	ds_bpermute_b32 v176, v235, v242
	v_mul_f32_e32 v180, 0x3fb8aa3b, v180
	v_cndmask_b32_e64 v215, 0, v182, s[44:45]
	v_exp_f32_e32 v239, v180
	v_add_f32_e32 v180, v183, v245
	v_add_f32_e32 v182, v184, v216
	v_add_f32_e32 v183, v240, v212
	v_add_f32_e32 v180, 0, v180
	v_add_f32_e32 v181, v242, v183
	v_add_f32_e32 v181, v181, v216
	v_add_f32_e32 v181, v181, v184
	v_cndmask_b32_e64 v173, 0, v216, s[10:11]
	s_waitcnt lgkmcnt(1)
	v_cndmask_b32_e64 v208, 0, v80, s[10:11]
	v_mul_f32_e32 v180, 0x3fb8aa3b, v180
	s_waitcnt lgkmcnt(0)
	v_add_f32_e32 v181, v181, v176
	v_exp_f32_e32 v241, v180
	v_add_f32_e32 v180, v162, v173
	v_add_f32_e32 v173, v183, v216
	v_add_f32_e32 v181, v208, v181
	v_cndmask_b32_e64 v186, 0, v176, s[10:11]
	v_add_f32_e32 v173, v173, v184
	v_add_f32_e32 v185, v162, v181
	v_add_f32_e32 v173, v186, v173
	v_add_f32_e32 v164, v164, v185
	v_add_f32_e32 v186, v174, v81
	v_add_f32_e32 v187, v166, v185
	v_add_f32_e32 v81, v81, v164
	v_add_f32_e32 v164, v167, v185
	v_add_f32_e32 v165, v165, v185
	v_add_f32_e32 v166, v186, v187
	v_add_f32_e32 v164, v175, v164
	v_add_f32_e32 v165, 0, v165
	v_mul_f32_e32 v166, 0x3fb8aa3b, v166
	v_mul_f32_e32 v164, 0x3fb8aa3b, v164
	v_mul_f32_e32 v165, 0x3fb8aa3b, v165
	v_exp_f32_e32 v166, v166
	v_exp_f32_e32 v164, v164
	v_exp_f32_e32 v165, v165
	v_cndmask_b32_e64 v174, 0, v166, s[30:31]
	v_cndmask_b32_e64 v175, 0, v164, s[26:27]
	v_cndmask_b32_e64 v181, 0, v165, s[38:39]
	v_add_f32_e32 v165, v162, v173
	v_add_f32_e32 v166, v178, v177
	v_add_f32_e32 v167, v168, v165
	v_mul_f32_e32 v81, 0x3fb8aa3b, v81
	v_add_f32_e32 v164, v166, v167
	v_add_f32_e32 v166, v170, v165
	v_add_f32_e32 v167, v169, v165
	v_add_f32_e32 v165, v171, v165
	v_add_f32_e32 v166, v177, v166
	v_add_f32_e32 v167, v179, v167
	v_add_f32_e32 v165, 0, v165
	v_mul_f32_e32 v164, 0x3fb8aa3b, v164
	v_mul_f32_e32 v166, 0x3fb8aa3b, v166
	v_mul_f32_e32 v167, 0x3fb8aa3b, v167
	v_mul_f32_e32 v165, 0x3fb8aa3b, v165
	v_exp_f32_e32 v81, v81
	v_exp_f32_e32 v164, v164
	v_exp_f32_e32 v166, v166
	v_exp_f32_e32 v167, v167
	v_exp_f32_e32 v165, v165
	v_cndmask_b32_e64 v81, 0, v81, s[40:41]
	v_cndmask_b32_e64 v168, 0, v164, s[22:23]
	v_cndmask_b32_e64 v166, 0, v166, s[34:35]
	v_cndmask_b32_e64 v167, 0, v167, s[18:19]
	v_cndmask_b32_e64 v169, 0, v165, s[28:29]
	v_cvt_pk_bf16_f32 v164, v174, v81
	v_cvt_pk_bf16_f32 v165, v175, v181
	v_cvt_pk_bf16_f32 v166, v168, v166
	v_cvt_pk_bf16_f32 v167, v167, v169
	s_nop 0
	s_nop 0
	v_mfma_f32_32x32x16_bf16 v[48:63], v[146:149], v[164:167], v[48:63]
	v_add_f32_e64 v146, v180, v188
	v_add_f32_e64 v147, v210, v209
	v_add_f32_e32 v81, v146, v147
	v_mul_f32_e32 v81, 0x3fb8aa3b, v81
	v_exp_f32_e32 v81, v81
	v_cndmask_b32_e32 v146, 0, v239, vcc
	v_cndmask_b32_e64 v81, 0, v81, s[36:37]
	v_mfma_f32_32x32x16_bf16 v[32:47], v[142:145], v[164:167], v[32:47]
	v_add_f32_e32 v143, v180, v190
	v_add_f32_e32 v144, v180, v189
	v_add_f32_e32 v143, v143, v209
	v_mul_f32_e32 v143, 0x3fb8aa3b, v143
	v_exp_f32_e32 v143, v143
	v_cndmask_b32_e64 v142, 0, v241, s[16:17]
	v_mfma_f32_32x32x16_bf16 v[16:31], v[138:141], v[164:167], v[16:31]
	v_add_f32_e32 v139, v180, v191
	v_add_f32_e32 v138, v144, v211
	v_add_f32_e32 v139, 0, v139
	v_mul_f32_e32 v138, 0x3fb8aa3b, v138
	v_mul_f32_e32 v139, 0x3fb8aa3b, v139
	v_exp_f32_e32 v138, v138
	v_exp_f32_e32 v139, v139
	v_mfma_f32_32x32x16_bf16 v[0:15], v[134:137], v[164:167], v[0:15]
	v_cndmask_b32_e64 v136, 0, v143, s[24:25]
	v_cndmask_b32_e64 v137, 0, v138, s[14:15]
	v_cndmask_b32_e64 v138, 0, v139, s[20:21]
	v_cvt_pk_bf16_f32 v134, v213, v215
	v_cvt_pk_bf16_f32 v135, v146, v142
	v_cvt_pk_bf16_f32 v136, v81, v136
	v_cvt_pk_bf16_f32 v137, v137, v138
	ds_read_b64_tr_b16 v[138:139], v207 offset:50240
	ds_read_b64_tr_b16 v[142:143], v207 offset:50304
	ds_read_b64_tr_b16 v[146:147], v207 offset:50368
	ds_read_b64_tr_b16 v[140:141], v207 offset:52800
	ds_read_b64_tr_b16 v[144:145], v207 offset:52864
	ds_read_b64_tr_b16 v[148:149], v207 offset:52928
	v_mfma_f32_32x32x16_bf16 v[48:63], v[130:133], v[134:137], v[48:63]
	v_mov_b32_e32 v130, v64
	v_mov_b32_e32 v131, v68
	v_mul_f32_e64 v132, v130, s68
	v_mul_f32_e64 v133, v131, s68
	v_mul_f32_e64 v64, |v132|, s54
	v_exp_f32_e32 v64, v64
	v_add_f32_e32 v80, v80, v176
	v_add_f32_e32 v81, v172, v242
	s_waitcnt lgkmcnt(2)
	v_mfma_f32_32x32x16_bf16 v[32:47], v[138:141], v[134:137], v[32:47]
	v_add_f32_e64 v80, v80, v182
	v_add_f32_e64 v81, v81, v183
	v_add_f32_e32 v64, 1.0, v64
	s_nop 1
	v_log_f32_e32 v138, v64
	v_min_f32_e32 v64, 0, v132
	s_waitcnt lgkmcnt(1)
	v_mfma_f32_32x32x16_bf16 v[16:31], v[142:145], v[134:137], v[16:31]
	v_mul_f32_e64 v143, |v133|, s54
	v_mul_f32_e32 v68, 0x3f317217, v138
	v_fma_f32 v132, v138, s86, -v68
	v_mov_b32_e32 v68, v65
	v_fmac_f32_e32 v132, 0x3377d1cf, v138
	v_fmac_f32_e32 v132, 0x3f317217, v138
	s_waitcnt lgkmcnt(0)
	v_mfma_f32_32x32x16_bf16 v[0:15], v[146:149], v[134:137], v[0:15]
	v_mul_f32_e64 v134, v68, s68
	v_mul_f32_e64 v135, v69, s68
	v_mul_f32_e64 v65, |v134|, s54
	v_exp_f32_e32 v65, v65
	v_mov_b32_e32 v137, v70
	v_exp_f32_e32 v143, v143
	v_min_f32_e32 v134, 0, v134
	v_add_f32_e32 v65, 1.0, v65
	v_add_f32_e32 v143, 1.0, v143
	s_nop 0
	v_log_f32_e32 v65, v65
	s_nop 0
	v_mul_f32_e32 v136, 0x3f317217, v65
	v_fma_f32 v140, v65, s86, -v136
	v_mov_b32_e32 v136, v66
	v_mul_f32_e32 v138, s68, v136
	v_mul_f32_e32 v139, s68, v137
	v_fmac_f32_e32 v140, 0x3377d1cf, v65
	v_mul_f32_e64 v66, |v138|, s54
	v_exp_f32_e32 v66, v66
	v_fmac_f32_e32 v140, 0x3f317217, v65
	v_min_f32_e32 v138, 0, v138
	v_add_f32_e32 v66, 1.0, v66
	v_mov_b32_e32 v65, v140
	s_nop 1
	v_log_f32_e32 v142, v66
	v_mov_b32_e32 v70, v67
	v_mul_f32_e32 v140, s68, v70
	v_mul_f32_e32 v141, s68, v71
	v_mul_f32_e64 v67, |v140|, s54
	v_exp_f32_e32 v67, v67
	v_mov_b32_e32 v66, v65
	v_mul_f32_e32 v65, 0x3f317217, v142
	v_fma_f32 v65, v142, s86, -v65
	v_fmac_f32_e32 v65, 0x3377d1cf, v142
	v_fmac_f32_e32 v65, 0x3f317217, v142
	v_add_f32_e32 v67, 1.0, v67
	v_min_f32_e32 v140, 0, v140
	s_nop 1
	v_log_f32_e32 v67, v67
	v_mov_b32_e32 v142, v65
	v_mul_f32_e32 v65, 0x3f317217, v67
	v_fma_f32 v65, v67, s86, -v65
	v_fmac_f32_e32 v65, 0x3377d1cf, v67
	v_fmac_f32_e32 v65, 0x3f317217, v67
	s_nop 1
	s_nop 0
	v_log_f32_e32 v143, v143
	v_mov_b32_e32 v144, v65
	v_min_f32_e32 v65, 0, v133
	v_or_b32_e32 v67, 8, v163
	v_mul_f32_e32 v133, 0x3f317217, v143
	v_fma_f32 v133, v143, s86, -v133
	v_fmac_f32_e32 v133, 0x3377d1cf, v143
	v_fmac_f32_e32 v133, 0x3f317217, v143
	s_nop 1
	v_sub_f32_e32 v64, v64, v132
	v_sub_f32_e32 v65, v65, v133
	v_mul_f32_e64 v132, |v135|, s54
	v_exp_f32_e32 v132, v132
	v_cmp_lt_i32_e32 vcc, v67, v153
	v_fma_f32 v130, -v130, s68, v64
	v_fma_f32 v131, -v131, s68, v65
	v_cmp_lt_i32_e64 s[14:15], v163, v152
	v_add_f32_e32 v67, 1.0, v132
	s_nop 0
	v_cndmask_b32_e64 v146, 0, v130, s[14:15]
	v_min_f32_e32 v135, 0, v135
	v_log_f32_e32 v67, v67
	v_cndmask_b32_e32 v147, 0, v131, vcc
	v_or_b32_e32 v131, 1, v163
	v_or_b32_e32 v130, 9, v163
	v_mul_f32_e32 v132, 0x3f317217, v67
	v_fma_f32 v132, v67, s86, -v132
	v_fmac_f32_e32 v132, 0x3377d1cf, v67
	v_fmac_f32_e32 v132, 0x3f317217, v67
	s_nop 1
	v_mov_b32_e32 v67, v132
	v_mul_f32_e64 v132, |v139|, s54
	v_sub_f32_e32 v66, v134, v66
	v_sub_f32_e32 v67, v135, v67
	v_exp_f32_e32 v134, v132
	v_fma_f32 v68, -v68, s68, v66
	v_fma_f32 v69, -v69, s68, v67
	v_cmp_lt_i32_e64 s[18:19], v131, v152
	v_cmp_lt_i32_e64 s[16:17], v130, v153
	v_min_f32_e32 v139, 0, v139
	v_cndmask_b32_e64 v132, 0, v68, s[18:19]
	v_add_f32_e32 v68, 1.0, v134
	v_cndmask_b32_e64 v133, 0, v69, s[16:17]
	v_or_b32_e32 v135, 2, v163
	v_log_f32_e32 v68, v68
	v_cmp_lt_i32_e64 s[24:25], v135, v152
	v_or_b32_e32 v134, 10, v163
	v_mul_f32_e32 v69, 0x3f317217, v68
	v_fma_f32 v69, v68, s86, -v69
	v_fmac_f32_e32 v69, 0x3377d1cf, v68
	v_fmac_f32_e32 v69, 0x3f317217, v68
	s_nop 1
	v_sub_f32_e32 v68, v138, v142
	v_sub_f32_e32 v69, v139, v69
	v_cmp_lt_i32_e64 s[22:23], v134, v153
	v_fma_f32 v130, -v136, s68, v68
	v_fma_f32 v131, -v137, s68, v69
	v_mul_f32_e64 v136, |v141|, s54
	v_exp_f32_e32 v136, v136
	v_cndmask_b32_e64 v142, 0, v130, s[24:25]
	v_cndmask_b32_e64 v143, 0, v131, s[22:23]
	v_mul_f32_e32 v134, s68, v72
	v_mul_f32_e32 v135, s68, v73
	v_add_f32_e32 v130, 1.0, v136
	v_mul_f32_e64 v138, |v134|, s54
	v_exp_f32_e32 v138, v138
	v_log_f32_e32 v130, v130
	v_or_b32_e32 v136, 11, v163
	v_or_b32_e32 v137, 3, v163
	v_cmp_lt_i32_e64 s[34:35], v137, v152
	v_mul_f32_e32 v131, 0x3f317217, v130
	v_fma_f32 v131, v130, s86, -v131
	v_fmac_f32_e32 v131, 0x3377d1cf, v130
	v_fmac_f32_e32 v131, 0x3f317217, v130
	v_min_f32_e32 v134, 0, v134
	v_min_f32_e32 v141, 0, v141
	v_cmp_lt_i32_e64 s[26:27], v136, v153
	v_add_f32_e32 v136, 1.0, v138
	v_sub_f32_e32 v130, v140, v144
	v_sub_f32_e32 v131, v141, v131
	v_log_f32_e32 v136, v136
	v_mul_f32_e64 v138, |v135|, s54
	v_exp_f32_e32 v138, v138
	v_min_f32_e32 v135, 0, v135
	v_mul_f32_e32 v137, 0x3f317217, v136
	v_fma_f32 v137, v136, s86, -v137
	v_fmac_f32_e32 v137, 0x3377d1cf, v136
	v_fmac_f32_e32 v137, 0x3f317217, v136
	v_or_b32_e32 v140, 16, v163
	v_cmp_lt_i32_e64 s[36:37], v140, v152
	v_mov_b32_e32 v136, v137
	v_add_f32_e32 v137, 1.0, v138
	v_fma_f32 v70, -v70, s68, v130
	v_fma_f32 v71, -v71, s68, v131
	s_nop 0
	v_log_f32_e32 v137, v137
	v_mov_b32_e32 v136, v136
	v_cndmask_b32_e64 v71, 0, v71, s[26:27]
	v_mul_f32_e32 v138, 0x3f317217, v137
	v_fma_f32 v138, v137, s86, -v138
	v_fmac_f32_e32 v138, 0x3377d1cf, v137
	v_fmac_f32_e32 v138, 0x3f317217, v137
	v_cndmask_b32_e64 v70, 0, v70, s[34:35]
	s_nop 0
	v_sub_f32_e32 v134, v134, v136
	v_sub_f32_e32 v135, v135, v138
	v_mul_f32_e32 v136, s68, v74
	v_mul_f32_e32 v137, s68, v75
	v_or_b32_e32 v138, 17, v163
	v_mul_f32_e64 v139, |v136|, s54
	v_exp_f32_e32 v139, v139
	v_cmp_lt_i32_e64 s[20:21], v138, v153
	v_mul_f32_e64 v140, |v137|, s54
	v_exp_f32_e32 v140, v140
	v_add_f32_e32 v138, 1.0, v139
	v_min_f32_e32 v136, 0, v136
	v_min_f32_e32 v137, 0, v137
	v_log_f32_e32 v138, v138
	v_fma_f32 v72, -v72, s68, v134
	v_fma_f32 v73, -v73, s68, v135
	v_mul_f32_e32 v139, 0x3f317217, v138
	v_fma_f32 v139, v138, s86, -v139
	v_fmac_f32_e32 v139, 0x3377d1cf, v138
	v_fmac_f32_e32 v139, 0x3f317217, v138
	v_cndmask_b32_e64 v73, 0, v73, s[20:21]
	v_cndmask_b32_e64 v72, 0, v72, s[36:37]
	v_mov_b32_e32 v138, v139
	v_add_f32_e32 v139, 1.0, v140
	s_nop 1
	v_log_f32_e32 v139, v139
	v_mov_b32_e32 v138, v138
	v_mul_f32_e32 v140, 0x3f317217, v139
	v_fma_f32 v140, v139, s86, -v140
	v_fmac_f32_e32 v140, 0x3377d1cf, v139
	v_fmac_f32_e32 v140, 0x3f317217, v139
	s_nop 1
	v_mov_b32_e32 v139, v140
	v_or_b32_e32 v140, 18, v163
	v_cmp_lt_i32_e64 s[30:31], v140, v152
	v_add_f32_e32 v140, v142, v70
	v_add_f32_e32 v141, v143, v71
	v_mov_b32_e32 v142, v76
	v_mov_b32_e32 v143, v78
	v_mul_f32_e32 v144, s68, v142
	v_mul_f32_e32 v145, s68, v143
	v_sub_f32_e32 v136, v136, v138
	v_sub_f32_e32 v137, v137, v139
	v_mul_f32_e64 v76, |v144|, s54
	v_exp_f32_e32 v78, v76
	v_or_b32_e32 v138, 19, v163
	v_fma_f32 v74, -v74, s68, v136
	v_fma_f32 v75, -v75, s68, v137
	v_cmp_lt_i32_e64 s[28:29], v138, v153
	v_cndmask_b32_e64 v138, 0, v74, s[30:31]
	v_mul_f32_e64 v149, |v145|, s54
	v_cndmask_b32_e64 v139, 0, v75, s[28:29]
	v_add_f32_e32 v74, v146, v132
	v_add_f32_e32 v75, v147, v133
	v_exp_f32_e32 v149, v149
	v_add_f32_e32 v146, v74, v140
	v_add_f32_e32 v147, v75, v141
	v_add_f32_e32 v74, 1.0, v78
	ds_bpermute_b32 v148, v235, v147
	ds_bpermute_b32 v76, v235, v146
	v_log_f32_e32 v75, v74
	s_nop 0
	v_mul_f32_e32 v78, 0x3f317217, v75
	v_add_f32_e32 v164, v72, v73
	v_add_f32_e32 v165, v73, v75
	v_min_f32_e32 v74, 0, v144
	v_fma_f32 v144, v75, s86, -v78
	v_mov_b32_e32 v78, v77
	v_mul_f32_e32 v166, s68, v78
	v_mul_f32_e32 v167, s68, v79
	v_fmac_f32_e32 v144, 0x3377d1cf, v75
	v_mul_f32_e64 v77, |v166|, s54
	v_exp_f32_e32 v77, v77
	v_fmac_f32_e32 v144, 0x3f317217, v75
	v_min_f32_e32 v166, 0, v166
	v_add_f32_e32 v77, 1.0, v77
	v_or_b32_e32 v165, 24, v163
	v_cmp_lt_i32_e64 s[42:43], v165, v152
	v_log_f32_e32 v77, v77
	v_mov_b32_e32 v144, v144
	v_mul_f32_e32 v75, 0x3f317217, v77
	v_fma_f32 v75, v77, s86, -v75
	v_fmac_f32_e32 v75, 0x3377d1cf, v77
	v_fmac_f32_e32 v75, 0x3f317217, v77
	s_nop 1
	v_mov_b32_e32 v168, v75
	v_add_f32_e32 v75, 1.0, v149
	v_or_b32_e32 v149, 26, v163
	s_nop 0
	v_log_f32_e32 v77, v75
	v_min_f32_e32 v75, 0, v145
	v_mul_f32_e32 v145, 0x3f317217, v77
	v_fma_f32 v145, v77, s86, -v145
	v_fmac_f32_e32 v145, 0x3377d1cf, v77
	v_fmac_f32_e32 v145, 0x3f317217, v77
	s_nop 1
	v_mov_b32_e32 v145, v145
	v_mul_f32_e64 v77, |v167|, s54
	v_exp_f32_e32 v77, v77
	v_sub_f32_e32 v74, v74, v144
	v_sub_f32_e32 v75, v75, v145
	v_min_f32_e32 v167, 0, v167
	v_cmp_lt_i32_e64 s[38:39], v149, v153
	v_add_f32_e32 v77, 1.0, v77
	v_or_b32_e32 v149, 27, v163
	v_or_b32_e32 v163, 25, v163
	v_log_f32_e32 v77, v77
	v_fma_f32 v142, -v142, s68, v74
	v_fma_f32 v143, -v143, s68, v75
	v_mul_f32_e32 v144, 0x3f317217, v77
	v_fma_f32 v144, v77, s86, -v144
	v_fmac_f32_e32 v144, 0x3377d1cf, v77
	v_fmac_f32_e32 v144, 0x3f317217, v77
	v_cndmask_b32_e64 v143, 0, v143, s[38:39]
	v_cndmask_b32_e64 v142, 0, v142, s[42:43]
	v_mov_b32_e32 v169, v144
	v_sub_f32_e32 v144, v166, v168
	v_sub_f32_e32 v145, v167, v169
	v_cmp_lt_i32_e64 s[40:41], v149, v153
	v_fma_f32 v78, -v78, s68, v144
	v_fma_f32 v79, -v79, s68, v145
	v_cmp_lt_i32_e64 s[44:45], v163, v152
	v_cndmask_b32_e64 v167, 0, v79, s[40:41]
	v_mov_b32_e32 v168, v132
	v_cndmask_b32_e64 v166, 0, v78, s[44:45]
	v_add_f32_e32 v142, v142, v166
	v_add_f32_e32 v143, v143, v167
	v_add_f32_e32 v170, v138, v139
	v_add_f32_e32 v171, v139, v133
	v_add_f32_e32 v164, v164, v170
	v_add_f32_e32 v165, v142, v143
	ds_bpermute_b32 v149, v235, v165
	ds_bpermute_b32 v77, v235, v164
	v_add_f32_e32 v78, v146, v146
	v_add_f32_e32 v79, v146, v147
	v_mov_b32_e32 v169, v64
	v_mov_b32_e32 v64, v133
	v_add_f32_e32 v132, v164, v165
	v_add_f32_e32 v133, v165, v164
	s_waitcnt lgkmcnt(1)
	v_add_f32_e32 v142, v165, v149
	s_waitcnt lgkmcnt(0)
	v_cndmask_b32_e64 v146, 0, v77, s[10:11]
	v_add_f32_e32 v142, v146, v142
	v_add_f32_e32 v146, v132, v149
	v_add_f32_e32 v147, v147, v132
	v_add_f32_e32 v146, v146, v77
	v_cndmask_b32_e64 v163, 0, v148, s[10:11]
	v_add_f32_e32 v147, v147, v149
	v_add_f32_e32 v146, v163, v146
	v_add_f32_e32 v147, v147, v77
	v_cndmask_b32_e64 v163, 0, v76, s[10:11]
	v_add_f32_e32 v76, v76, v148
	v_add_f32_e32 v77, v77, v149
	v_mov_b32_e32 v78, v80
	v_add_f32_e32 v147, v147, v148
	v_add_f32_e32 v77, v76, v77
	v_add_f32_e32 v76, v76, v76
	v_pk_mov_b32 v[80:81], v[80:81], v[132:133] op_sel:[1,0]
	v_add_f32_e32 v147, v163, v147
	v_add_f32_e32 v78, v78, v80
	v_add_f32_e32 v79, v79, v81
	v_mov_b32_e32 v163, v77
	v_add_f32_e32 v80, v162, v78
	v_add_f32_e32 v81, v163, v79
	v_add_f32_e32 v77, v80, v147
	v_add_f32_e32 v78, v168, v140
	v_add_f32_e32 v79, v169, v77
	v_add_f32_e32 v68, v68, v77
	v_add_f32_e32 v76, v78, v79
	v_mul_f32_e32 v76, 0x3fb8aa3b, v76
	v_exp_f32_e32 v76, v76
	v_add_f32_e32 v66, v66, v77
	v_add_f32_e32 v68, v70, v68
	v_add_f32_e32 v70, v130, v77
	v_cndmask_b32_e64 v78, 0, v76, s[14:15]
	v_add_f32_e32 v77, v80, v146
	v_add_f32_e32 v66, v140, v66
	v_add_f32_e32 v64, v64, v141
	v_add_f32_e32 v65, v65, v77
	v_mul_f32_e32 v66, 0x3fb8aa3b, v66
	v_add_f32_e32 v64, v64, v65
	v_add_f32_e32 v65, v67, v77
	v_exp_f32_e32 v66, v66
	v_add_f32_e32 v65, v141, v65
	v_mul_f32_e32 v64, 0x3fb8aa3b, v64
	v_mul_f32_e32 v65, 0x3fb8aa3b, v65
	v_exp_f32_e32 v64, v64
	v_exp_f32_e32 v65, v65
	v_cndmask_b32_e64 v79, 0, v66, s[18:19]
	v_add_f32_e32 v66, v69, v77
	v_add_f32_e32 v66, v71, v66
	v_mul_f32_e32 v66, 0x3fb8aa3b, v66
	v_cndmask_b32_e32 v71, 0, v64, vcc
	v_cndmask_b32_e64 v76, 0, v65, s[16:17]
	v_add_f32_e32 v171, v80, v142
	v_pk_mov_b32 v[64:65], v[72:73], v[134:135] op_sel:[1,0]
	v_exp_f32_e32 v66, v66
	v_add_f32_e32 v67, v131, v77
	v_add_f32_e32 v64, v64, v170
	v_add_f32_e32 v65, v65, v171
	v_add_f32_e32 v67, 0, v67
	v_add_f32_e32 v64, v64, v65
	v_add_f32_e32 v65, v135, v171
	v_mul_f32_e32 v67, 0x3fb8aa3b, v67
	v_mul_f32_e32 v64, 0x3fb8aa3b, v64
	v_add_f32_e32 v65, v170, v65
	v_exp_f32_e32 v67, v67
	v_exp_f32_e32 v64, v64
	v_mul_f32_e32 v65, 0x3fb8aa3b, v65
	v_add_f32_e32 v70, 0, v70
	v_cndmask_b32_e64 v77, 0, v66, s[22:23]
	v_exp_f32_e32 v140, v65
	v_add_f32_e32 v65, v136, v171
	v_add_f32_e32 v66, v137, v171
	v_mul_f32_e32 v68, 0x3fb8aa3b, v68
	v_mul_f32_e32 v70, 0x3fb8aa3b, v70
	v_add_f32_e32 v65, v139, v65
	v_add_f32_e32 v66, 0, v66
	v_exp_f32_e32 v68, v68
	v_exp_f32_e32 v70, v70
	v_mul_f32_e32 v65, 0x3fb8aa3b, v65
	v_mul_f32_e32 v66, 0x3fb8aa3b, v66
	v_cndmask_b32_e64 v131, 0, v67, s[26:27]
	v_exp_f32_e32 v139, v66
	v_exp_f32_e32 v141, v65
	v_cndmask_b32_e64 v146, 0, v64, s[36:37]
	ds_read_b64_tr_b16 v[64:65], v207 offset:34816
	ds_read_b64_tr_b16 v[66:67], v207 offset:37376
	v_cndmask_b32_e64 v138, 0, v149, s[10:11]
	v_add_f32_e32 v72, v80, v138
	v_mov_b32_e32 v142, v74
	v_cndmask_b32_e64 v130, 0, v68, s[24:25]
	v_cndmask_b32_e64 v70, 0, v70, s[34:35]
	v_add_f32_e32 v68, v72, v142
	v_add_f32_e32 v69, v166, v143
	v_cndmask_b32_e64 v74, 0, v139, s[28:29]
	v_add_f32_e32 v73, v68, v69
	v_cvt_pk_bf16_f32 v68, v78, v79
	v_cvt_pk_bf16_f32 v69, v130, v70
	v_cvt_pk_bf16_f32 v70, v71, v76
	v_cvt_pk_bf16_f32 v71, v77, v131
	ds_read_b64_tr_b16 v[76:77], v207 offset:34880
	ds_read_b64_tr_b16 v[130:131], v207 offset:34944
	ds_read_b64_tr_b16 v[134:135], v207 offset:35008
	ds_read_b64_tr_b16 v[78:79], v207 offset:37440
	ds_read_b64_tr_b16 v[132:133], v207 offset:37504
	ds_read_b64_tr_b16 v[136:137], v207 offset:37568
	s_waitcnt lgkmcnt(6)
	v_mfma_f32_32x32x16_bf16 v[48:63], v[64:67], v[68:71], v[48:63]
	v_mul_f32_e32 v64, 0x3fb8aa3b, v73
	v_exp_f32_e32 v64, v64
	v_add_f32_e32 v65, v72, v75
	v_add_f32_e32 v65, v65, v167
	v_mul_f32_e32 v65, 0x3fb8aa3b, v65
	v_cndmask_b32_e64 v139, 0, v64, s[42:43]
	v_add_f32_e32 v64, v72, v144
	v_exp_f32_e32 v75, v65
	v_add_f32_e32 v65, v72, v145
	v_add_f32_e32 v64, v64, v143
	v_add_f32_e32 v65, 0, v65
	v_mul_f32_e32 v64, 0x3fb8aa3b, v64
	v_mul_f32_e32 v65, 0x3fb8aa3b, v65
	v_exp_f32_e32 v64, v64
	v_exp_f32_e32 v72, v65
	s_waitcnt lgkmcnt(2)
	v_mfma_f32_32x32x16_bf16 v[32:47], v[76:79], v[68:71], v[32:47]
	v_cndmask_b32_e64 v73, 0, v140, s[20:21]
	v_cndmask_b32_e64 v138, 0, v141, s[30:31]
	v_cndmask_b32_e64 v76, 0, v64, s[44:45]
	v_cndmask_b32_e64 v72, 0, v72, s[40:41]
	ds_read_b64_tr_b16 v[64:65], v207 offset:39936
	ds_read_b64_tr_b16 v[66:67], v207 offset:42496
	v_add_f32_e32 v162, v80, v81
	s_mov_b32 s14, 0xc2480000
	s_waitcnt lgkmcnt(3)
	v_mfma_f32_32x32x16_bf16 v[16:31], v[130:133], v[68:71], v[16:31]
	v_cmp_gt_f32_e32 vcc, s14, v162
	s_cmp_eq_u64 vcc, exec
	s_cselect_b64 s[14:15], -1, 0
	s_waitcnt lgkmcnt(2)
	v_mfma_f32_32x32x16_bf16 v[0:15], v[134:137], v[68:71], v[0:15]
	v_cndmask_b32_e64 v71, 0, v75, s[38:39]
	v_cvt_pk_bf16_f32 v68, v146, v73
	v_cvt_pk_bf16_f32 v69, v138, v74
	v_cvt_pk_bf16_f32 v70, v139, v76
	v_cvt_pk_bf16_f32 v71, v71, v72
	ds_read_b64_tr_b16 v[72:73], v207 offset:40000
	ds_read_b64_tr_b16 v[76:77], v207 offset:40064
	ds_read_b64_tr_b16 v[130:131], v207 offset:40128
	ds_read_b64_tr_b16 v[74:75], v207 offset:42560
	ds_read_b64_tr_b16 v[78:79], v207 offset:42624
	ds_read_b64_tr_b16 v[132:133], v207 offset:42688
	s_waitcnt lgkmcnt(6)
	v_mfma_f32_32x32x16_bf16 v[48:63], v[64:67], v[68:71], v[48:63]
	s_waitcnt lgkmcnt(2)
	v_mfma_f32_32x32x16_bf16 v[32:47], v[72:75], v[68:71], v[32:47]
	s_waitcnt lgkmcnt(1)
	v_mfma_f32_32x32x16_bf16 v[16:31], v[76:79], v[68:71], v[16:31]
	s_waitcnt lgkmcnt(0)
	v_mfma_f32_32x32x16_bf16 v[0:15], v[130:133], v[68:71], v[0:15]
